# FFN-in leftover tiles cut into 64x64 pieces handed out through per-XCD counters (work stealing at the tail of the phase)
# baseline (speedup 1.0000x reference)
.Lfi_main_done:
	v_readlane_b32 s40, v239, 0
	s_cmp_eq_u32 s40, 2112
	s_cbranch_scc1 .Lfi_done
	v_and_b32_e32 v225, 63, v170
	v_lshrrev_b32_e32 v226, 6, v170
	v_and_b32_e32 v229, 15, v225
	v_lshrrev_b32_e32 v230, 4, v225
	v_lshlrev_b32_e32 v231, 10, v226
	v_lshrrev_b32_e32 v232, 3, v170
	v_readfirstlane_b32 s52, v231
	v_and_b32_e32 v233, 7, v170
	v_bfe_u32 v224, v232, 1, 3
	v_xor_b32_e32 v233, v233, v224
	v_lshlrev_b32_e32 v233, 4, v233
	s_movk_i32 s4, 0x880
	v_mad_u32_u24 v224, v232, s4, v233
	v_and_b32_e32 v233, 15, v232
	v_lshlrev_b32_e32 v233, 1, v233
	v_lshrrev_b32_e32 v168, 4, v232
	v_add_u32_e32 v233, v233, v168
	v_and_b32_e32 v168, 7, v170
	v_bfe_u32 v169, v232, 1, 3
	v_xor_b32_e32 v168, v168, v169
	v_lshlrev_b32_e32 v168, 4, v168
	v_mad_u32_u24 v168, v233, s4, v168
	v_bfe_u32 v233, v229, 1, 3
	v_xor_b32_e32 v231, v230, v233
	v_or_b32_e32 v232, 4, v230
	v_xor_b32_e32 v232, v232, v233
	v_lshlrev_b32_e32 v231, 4, v231
	v_lshlrev_b32_e32 v232, 4, v232
	v_lshl_add_u32 v233, v226, 4, v229
	v_lshlrev_b32_e32 v233, 7, v233
	v_add_u32_e32 v220, v233, v231
	v_add_u32_e32 v221, v233, v232
	v_mov_b32_e32 v233, v229
	v_lshlrev_b32_e32 v233, 7, v233
	v_add_u32_e32 v233, 0x2000, v233
	v_add_u32_e32 v222, v233, v231
	v_add_u32_e32 v223, v233, v232
	v_lshlrev_b32_e32 v233, 4, v226
	v_lshl_add_u32 v233, v230, 2, v233
	v_lshlrev_b32_e32 v227, 2, v229
	s_movk_i32 s4, 0x1680
	v_mad_u32_u24 v225, v233, s4, v227
.Lfp_next:
	s_barrier
	s_cmp_lg_u32 s52, 0
	s_cbranch_scc1 .Lfp_notw0
	v_readlane_b32 s4, v235, 34
	v_readlane_b32 s5, v235, 35
	v_readlane_b32 s55, v237, 0
	s_and_b32 s55, s55, 7
	s_lshl_b32 s55, s55, 2
	v_readlane_b32 s56, v235, 46
	s_lshl_b32 s56, s56, 8
	s_add_u32 s55, s55, s56
	s_add_u32 s55, s55, 0x4000
	s_mov_b64 s[40:41], exec
	s_mov_b64 exec, 1
	v_mov_b32_e32 v226, s55
	v_mov_b32_e32 v227, 1
	global_atomic_add v228, v226, v227, s[4:5] sc0
	s_waitcnt vmcnt(0)
	v_mov_b32_e32 v226, 0xfffc
	ds_write_b32 v226, v228
	s_waitcnt lgkmcnt(0)
	s_mov_b64 exec, s[40:41]
.Lfp_notw0:
	s_barrier
	v_mov_b32_e32 v226, 0xfffc
	ds_read_b32 v228, v226
	s_waitcnt lgkmcnt(0)
	v_readfirstlane_b32 s55, v228
	s_cmp_ge_u32 s55, 64
	s_cbranch_scc1 .Lfi_done
	s_and_b32 s56, s55, 7
	s_lshr_b32 s54, s55, 3
	s_lshl_b32 s54, s54, 3
	v_readlane_b32 s57, v237, 0
	s_and_b32 s57, s57, 7
	s_add_u32 s54, s54, s57
	s_add_u32 s54, s54, 2048
	s_lshr_b32 s55, s54, 4
	s_mul_hi_u32 s55, s55, 0x55555556
	s_mul_i32 s53, s55, 48
	s_sub_u32 s53, s54, s53
	v_readlane_b32 s4, v235, 34
	v_readlane_b32 s5, v235, 35
	s_mul_i32 s44, s53, 0x88000
	s_add_u32 s44, s44, 0xe166000
	s_add_u32 s44, s44, s4
	s_addc_u32 s45, s5, 0
	s_mul_i32 s46, s55, 0x44000
	s_lshr_b32 s57, s56, 1
	s_mul_i32 s57, s57, 0x22000
	s_add_u32 s44, s44, s57
	s_addc_u32 s45, s45, 0
	s_and_b32 s57, s56, 1
	s_mul_i32 s57, s57, 0x22000
	s_add_u32 s46, s46, s57
	s_add_u32 s46, s46, s36
	s_addc_u32 s47, s37, 0
	s_lshr_b32 s55, s54, 4
	s_mul_hi_u32 s55, s55, 0x55555556
	s_mul_i32 s53, s55, 48
	s_sub_u32 s53, s54, s53
	v_readlane_b32 s4, v235, 34
	v_readlane_b32 s5, v235, 35
	s_mul_i32 s50, s53, 0x168000
	s_lshl_b32 s55, s55, 7
	s_add_u32 s50, s50, s55
	s_add_u32 s50, s50, 0xfae6000
	s_and_b32 s57, s56, 1
	s_lshl_b32 s57, s57, 6
	s_add_u32 s50, s50, s57
	s_lshr_b32 s57, s56, 1
	s_mul_i32 s57, s57, 0x5a000
	s_add_u32 s50, s50, s57
	s_add_u32 s50, s50, s4
	s_addc_u32 s51, s5, 0
	v_mov_b32_e32 v0, 0
	v_mov_b32_e32 v1, 0
	v_mov_b32_e32 v2, 0
	v_mov_b32_e32 v3, 0
	v_mov_b32_e32 v4, 0
	v_mov_b32_e32 v5, 0
	v_mov_b32_e32 v6, 0
	v_mov_b32_e32 v7, 0
	v_mov_b32_e32 v8, 0
	v_mov_b32_e32 v9, 0
	v_mov_b32_e32 v10, 0
	v_mov_b32_e32 v11, 0
	v_mov_b32_e32 v12, 0
	v_mov_b32_e32 v13, 0
	v_mov_b32_e32 v14, 0
	v_mov_b32_e32 v15, 0
	s_add_u32 m0, s52, 0x0
	s_add_u32 s4, s44, 0x0
	s_addc_u32 s5, s45, 0
	global_load_lds_dwordx4 v224, s[4:5]
	s_add_u32 m0, s52, 0x1000
	s_add_u32 s4, s44, 0x11000
	s_addc_u32 s5, s45, 0
	global_load_lds_dwordx4 v224, s[4:5]
	s_add_u32 m0, s52, 0x2000
	s_add_u32 s4, s46, 0x0
	s_addc_u32 s5, s47, 0
	global_load_lds_dwordx4 v168, s[4:5]
	s_add_u32 m0, s52, 0x3000
	s_add_u32 s4, s46, 0x11000
	s_addc_u32 s5, s47, 0
	global_load_lds_dwordx4 v168, s[4:5]
	s_add_u32 s44, s44, 0x80
	s_addc_u32 s45, s45, 0
	s_add_u32 s46, s46, 0x80
	s_addc_u32 s47, s47, 0
	s_add_u32 m0, s52, 0x4000
	s_add_u32 s4, s44, 0x0
	s_addc_u32 s5, s45, 0
	global_load_lds_dwordx4 v224, s[4:5]
	s_add_u32 m0, s52, 0x5000
	s_add_u32 s4, s44, 0x11000
	s_addc_u32 s5, s45, 0
	global_load_lds_dwordx4 v224, s[4:5]
	s_add_u32 m0, s52, 0x6000
	s_add_u32 s4, s46, 0x0
	s_addc_u32 s5, s47, 0
	global_load_lds_dwordx4 v168, s[4:5]
	s_add_u32 m0, s52, 0x7000
	s_add_u32 s4, s46, 0x11000
	s_addc_u32 s5, s47, 0
	global_load_lds_dwordx4 v168, s[4:5]
	s_add_u32 s44, s44, 0x80
	s_addc_u32 s45, s45, 0
	s_add_u32 s46, s46, 0x80
	s_addc_u32 s47, s47, 0
	s_add_u32 m0, s52, 0x8000
	s_add_u32 s4, s44, 0x0
	s_addc_u32 s5, s45, 0
	global_load_lds_dwordx4 v224, s[4:5]
	s_add_u32 m0, s52, 0x9000
	s_add_u32 s4, s44, 0x11000
	s_addc_u32 s5, s45, 0
	global_load_lds_dwordx4 v224, s[4:5]
	s_add_u32 m0, s52, 0xa000
	s_add_u32 s4, s46, 0x0
	s_addc_u32 s5, s47, 0
	global_load_lds_dwordx4 v168, s[4:5]
	s_add_u32 m0, s52, 0xb000
	s_add_u32 s4, s46, 0x11000
	s_addc_u32 s5, s47, 0
	global_load_lds_dwordx4 v168, s[4:5]
	s_add_u32 s44, s44, 0x80
	s_addc_u32 s45, s45, 0
	s_add_u32 s46, s46, 0x80
	s_addc_u32 s47, s47, 0
	s_waitcnt vmcnt(8)
	s_barrier
	s_add_u32 m0, s52, 0xc000
	s_add_u32 s4, s44, 0x0
	s_addc_u32 s5, s45, 0
	global_load_lds_dwordx4 v224, s[4:5]
	s_add_u32 m0, s52, 0xd000
	s_add_u32 s4, s44, 0x11000
	s_addc_u32 s5, s45, 0
	global_load_lds_dwordx4 v224, s[4:5]
	s_add_u32 m0, s52, 0xe000
	s_add_u32 s4, s46, 0x0
	s_addc_u32 s5, s47, 0
	global_load_lds_dwordx4 v168, s[4:5]
	s_add_u32 m0, s52, 0xf000
	s_add_u32 s4, s46, 0x11000
	s_addc_u32 s5, s47, 0
	global_load_lds_dwordx4 v168, s[4:5]
	s_add_u32 s44, s44, 0x80
	s_addc_u32 s45, s45, 0
	s_add_u32 s46, s46, 0x80
	s_addc_u32 s47, s47, 0
	ds_read_b128 v[204:207], v222
	ds_read_b128 v[208:211], v222 offset:2048
	ds_read_b128 v[212:215], v222 offset:4096
	ds_read_b128 v[216:219], v222 offset:6144
	ds_read_b128 v[136:139], v220
	ds_read_b128 a[0:3], v223
	ds_read_b128 a[4:7], v223 offset:2048
	ds_read_b128 a[8:11], v223 offset:4096
	ds_read_b128 a[12:15], v223 offset:6144
	ds_read_b128 v[140:143], v221
	s_waitcnt lgkmcnt(5)
	v_mfma_f32_16x16x32_bf16 v[0:3], v[136:139], v[204:207], v[0:3]
	v_mfma_f32_16x16x32_bf16 v[4:7], v[136:139], v[208:211], v[4:7]
	v_mfma_f32_16x16x32_bf16 v[8:11], v[136:139], v[212:215], v[8:11]
	v_mfma_f32_16x16x32_bf16 v[12:15], v[136:139], v[216:219], v[12:15]
	s_waitcnt lgkmcnt(0)
	v_mfma_f32_16x16x32_bf16 v[0:3], v[140:143], a[0:3], v[0:3]
	v_mfma_f32_16x16x32_bf16 v[4:7], v[140:143], a[4:7], v[4:7]
	v_mfma_f32_16x16x32_bf16 v[8:11], v[140:143], a[8:11], v[8:11]
	v_mfma_f32_16x16x32_bf16 v[12:15], v[140:143], a[12:15], v[12:15]
	s_waitcnt vmcnt(8)
	s_barrier
	s_add_u32 m0, s52, 0x0
	s_add_u32 s4, s44, 0x0
	s_addc_u32 s5, s45, 0
	global_load_lds_dwordx4 v224, s[4:5]
	s_add_u32 m0, s52, 0x1000
	s_add_u32 s4, s44, 0x11000
	s_addc_u32 s5, s45, 0
	global_load_lds_dwordx4 v224, s[4:5]
	s_add_u32 m0, s52, 0x2000
	s_add_u32 s4, s46, 0x0
	s_addc_u32 s5, s47, 0
	global_load_lds_dwordx4 v168, s[4:5]
	s_add_u32 m0, s52, 0x3000
	s_add_u32 s4, s46, 0x11000
	s_addc_u32 s5, s47, 0
	global_load_lds_dwordx4 v168, s[4:5]
	s_add_u32 s44, s44, 0x80
	s_addc_u32 s45, s45, 0
	s_add_u32 s46, s46, 0x80
	s_addc_u32 s47, s47, 0
	ds_read_b128 v[204:207], v222 offset:16384
	ds_read_b128 v[208:211], v222 offset:18432
	ds_read_b128 v[212:215], v222 offset:20480
	ds_read_b128 v[216:219], v222 offset:22528
	ds_read_b128 v[136:139], v220 offset:16384
	ds_read_b128 a[0:3], v223 offset:16384
	ds_read_b128 a[4:7], v223 offset:18432
	ds_read_b128 a[8:11], v223 offset:20480
	ds_read_b128 a[12:15], v223 offset:22528
	ds_read_b128 v[140:143], v221 offset:16384
	s_waitcnt lgkmcnt(5)
	v_mfma_f32_16x16x32_bf16 v[0:3], v[136:139], v[204:207], v[0:3]
	v_mfma_f32_16x16x32_bf16 v[4:7], v[136:139], v[208:211], v[4:7]
	v_mfma_f32_16x16x32_bf16 v[8:11], v[136:139], v[212:215], v[8:11]
	v_mfma_f32_16x16x32_bf16 v[12:15], v[136:139], v[216:219], v[12:15]
	s_waitcnt lgkmcnt(0)
	v_mfma_f32_16x16x32_bf16 v[0:3], v[140:143], a[0:3], v[0:3]
	v_mfma_f32_16x16x32_bf16 v[4:7], v[140:143], a[4:7], v[4:7]
	v_mfma_f32_16x16x32_bf16 v[8:11], v[140:143], a[8:11], v[8:11]
	v_mfma_f32_16x16x32_bf16 v[12:15], v[140:143], a[12:15], v[12:15]
	s_waitcnt vmcnt(8)
	s_barrier
	s_add_u32 m0, s52, 0x4000
	s_add_u32 s4, s44, 0x0
	s_addc_u32 s5, s45, 0
	global_load_lds_dwordx4 v224, s[4:5]
	s_add_u32 m0, s52, 0x5000
	s_add_u32 s4, s44, 0x11000
	s_addc_u32 s5, s45, 0
	global_load_lds_dwordx4 v224, s[4:5]
	s_add_u32 m0, s52, 0x6000
	s_add_u32 s4, s46, 0x0
	s_addc_u32 s5, s47, 0
	global_load_lds_dwordx4 v168, s[4:5]
	s_add_u32 m0, s52, 0x7000
	s_add_u32 s4, s46, 0x11000
	s_addc_u32 s5, s47, 0
	global_load_lds_dwordx4 v168, s[4:5]
	s_add_u32 s44, s44, 0x80
	s_addc_u32 s45, s45, 0
	s_add_u32 s46, s46, 0x80
	s_addc_u32 s47, s47, 0
	ds_read_b128 v[204:207], v222 offset:32768
	ds_read_b128 v[208:211], v222 offset:34816
	ds_read_b128 v[212:215], v222 offset:36864
	ds_read_b128 v[216:219], v222 offset:38912
	ds_read_b128 v[136:139], v220 offset:32768
	ds_read_b128 a[0:3], v223 offset:32768
	ds_read_b128 a[4:7], v223 offset:34816
	ds_read_b128 a[8:11], v223 offset:36864
	ds_read_b128 a[12:15], v223 offset:38912
	ds_read_b128 v[140:143], v221 offset:32768
	s_waitcnt lgkmcnt(5)
	v_mfma_f32_16x16x32_bf16 v[0:3], v[136:139], v[204:207], v[0:3]
	v_mfma_f32_16x16x32_bf16 v[4:7], v[136:139], v[208:211], v[4:7]
	v_mfma_f32_16x16x32_bf16 v[8:11], v[136:139], v[212:215], v[8:11]
	v_mfma_f32_16x16x32_bf16 v[12:15], v[136:139], v[216:219], v[12:15]
	s_waitcnt lgkmcnt(0)
	v_mfma_f32_16x16x32_bf16 v[0:3], v[140:143], a[0:3], v[0:3]
	v_mfma_f32_16x16x32_bf16 v[4:7], v[140:143], a[4:7], v[4:7]
	v_mfma_f32_16x16x32_bf16 v[8:11], v[140:143], a[8:11], v[8:11]
	v_mfma_f32_16x16x32_bf16 v[12:15], v[140:143], a[12:15], v[12:15]
	s_waitcnt vmcnt(8)
	s_barrier
	s_add_u32 m0, s52, 0x8000
	s_add_u32 s4, s44, 0x0
	s_addc_u32 s5, s45, 0
	global_load_lds_dwordx4 v224, s[4:5]
	s_add_u32 m0, s52, 0x9000
	s_add_u32 s4, s44, 0x11000
	s_addc_u32 s5, s45, 0
	global_load_lds_dwordx4 v224, s[4:5]
	s_add_u32 m0, s52, 0xa000
	s_add_u32 s4, s46, 0x0
	s_addc_u32 s5, s47, 0
	global_load_lds_dwordx4 v168, s[4:5]
	s_add_u32 m0, s52, 0xb000
	s_add_u32 s4, s46, 0x11000
	s_addc_u32 s5, s47, 0
	global_load_lds_dwordx4 v168, s[4:5]
	s_add_u32 s44, s44, 0x80
	s_addc_u32 s45, s45, 0
	s_add_u32 s46, s46, 0x80
	s_addc_u32 s47, s47, 0
	ds_read_b128 v[204:207], v222 offset:49152
	ds_read_b128 v[208:211], v222 offset:51200
	ds_read_b128 v[212:215], v222 offset:53248
	ds_read_b128 v[216:219], v222 offset:55296
	ds_read_b128 v[136:139], v220 offset:49152
	ds_read_b128 a[0:3], v223 offset:49152
	ds_read_b128 a[4:7], v223 offset:51200
	ds_read_b128 a[8:11], v223 offset:53248
	ds_read_b128 a[12:15], v223 offset:55296
	ds_read_b128 v[140:143], v221 offset:49152
	s_waitcnt lgkmcnt(5)
	v_mfma_f32_16x16x32_bf16 v[0:3], v[136:139], v[204:207], v[0:3]
	v_mfma_f32_16x16x32_bf16 v[4:7], v[136:139], v[208:211], v[4:7]
	v_mfma_f32_16x16x32_bf16 v[8:11], v[136:139], v[212:215], v[8:11]
	v_mfma_f32_16x16x32_bf16 v[12:15], v[136:139], v[216:219], v[12:15]
	s_waitcnt lgkmcnt(0)
	v_mfma_f32_16x16x32_bf16 v[0:3], v[140:143], a[0:3], v[0:3]
	v_mfma_f32_16x16x32_bf16 v[4:7], v[140:143], a[4:7], v[4:7]
	v_mfma_f32_16x16x32_bf16 v[8:11], v[140:143], a[8:11], v[8:11]
	v_mfma_f32_16x16x32_bf16 v[12:15], v[140:143], a[12:15], v[12:15]
	s_waitcnt vmcnt(8)
	s_barrier
	s_add_u32 m0, s52, 0xc000
	s_add_u32 s4, s44, 0x0
	s_addc_u32 s5, s45, 0
	global_load_lds_dwordx4 v224, s[4:5]
	s_add_u32 m0, s52, 0xd000
	s_add_u32 s4, s44, 0x11000
	s_addc_u32 s5, s45, 0
	global_load_lds_dwordx4 v224, s[4:5]
	s_add_u32 m0, s52, 0xe000
	s_add_u32 s4, s46, 0x0
	s_addc_u32 s5, s47, 0
	global_load_lds_dwordx4 v168, s[4:5]
	s_add_u32 m0, s52, 0xf000
	s_add_u32 s4, s46, 0x11000
	s_addc_u32 s5, s47, 0
	global_load_lds_dwordx4 v168, s[4:5]
	s_add_u32 s44, s44, 0x80
	s_addc_u32 s45, s45, 0
	s_add_u32 s46, s46, 0x80
	s_addc_u32 s47, s47, 0
	ds_read_b128 v[204:207], v222
	ds_read_b128 v[208:211], v222 offset:2048
	ds_read_b128 v[212:215], v222 offset:4096
	ds_read_b128 v[216:219], v222 offset:6144
	ds_read_b128 v[136:139], v220
	ds_read_b128 a[0:3], v223
	ds_read_b128 a[4:7], v223 offset:2048
	ds_read_b128 a[8:11], v223 offset:4096
	ds_read_b128 a[12:15], v223 offset:6144
	ds_read_b128 v[140:143], v221
	s_waitcnt lgkmcnt(5)
	v_mfma_f32_16x16x32_bf16 v[0:3], v[136:139], v[204:207], v[0:3]
	v_mfma_f32_16x16x32_bf16 v[4:7], v[136:139], v[208:211], v[4:7]
	v_mfma_f32_16x16x32_bf16 v[8:11], v[136:139], v[212:215], v[8:11]
	v_mfma_f32_16x16x32_bf16 v[12:15], v[136:139], v[216:219], v[12:15]
	s_waitcnt lgkmcnt(0)
	v_mfma_f32_16x16x32_bf16 v[0:3], v[140:143], a[0:3], v[0:3]
	v_mfma_f32_16x16x32_bf16 v[4:7], v[140:143], a[4:7], v[4:7]
	v_mfma_f32_16x16x32_bf16 v[8:11], v[140:143], a[8:11], v[8:11]
	v_mfma_f32_16x16x32_bf16 v[12:15], v[140:143], a[12:15], v[12:15]
	s_waitcnt vmcnt(8)
	s_barrier
	s_add_u32 m0, s52, 0x0
	s_add_u32 s4, s44, 0x0
	s_addc_u32 s5, s45, 0
	global_load_lds_dwordx4 v224, s[4:5]
	s_add_u32 m0, s52, 0x1000
	s_add_u32 s4, s44, 0x11000
	s_addc_u32 s5, s45, 0
	global_load_lds_dwordx4 v224, s[4:5]
	s_add_u32 m0, s52, 0x2000
	s_add_u32 s4, s46, 0x0
	s_addc_u32 s5, s47, 0
	global_load_lds_dwordx4 v168, s[4:5]
	s_add_u32 m0, s52, 0x3000
	s_add_u32 s4, s46, 0x11000
	s_addc_u32 s5, s47, 0
	global_load_lds_dwordx4 v168, s[4:5]
	s_add_u32 s44, s44, 0x80
	s_addc_u32 s45, s45, 0
	s_add_u32 s46, s46, 0x80
	s_addc_u32 s47, s47, 0
	ds_read_b128 v[204:207], v222 offset:16384
	ds_read_b128 v[208:211], v222 offset:18432
	ds_read_b128 v[212:215], v222 offset:20480
	ds_read_b128 v[216:219], v222 offset:22528
	ds_read_b128 v[136:139], v220 offset:16384
	ds_read_b128 a[0:3], v223 offset:16384
	ds_read_b128 a[4:7], v223 offset:18432
	ds_read_b128 a[8:11], v223 offset:20480
	ds_read_b128 a[12:15], v223 offset:22528
	ds_read_b128 v[140:143], v221 offset:16384
	s_waitcnt lgkmcnt(5)
	v_mfma_f32_16x16x32_bf16 v[0:3], v[136:139], v[204:207], v[0:3]
	v_mfma_f32_16x16x32_bf16 v[4:7], v[136:139], v[208:211], v[4:7]
	v_mfma_f32_16x16x32_bf16 v[8:11], v[136:139], v[212:215], v[8:11]
	v_mfma_f32_16x16x32_bf16 v[12:15], v[136:139], v[216:219], v[12:15]
	s_waitcnt lgkmcnt(0)
	v_mfma_f32_16x16x32_bf16 v[0:3], v[140:143], a[0:3], v[0:3]
	v_mfma_f32_16x16x32_bf16 v[4:7], v[140:143], a[4:7], v[4:7]
	v_mfma_f32_16x16x32_bf16 v[8:11], v[140:143], a[8:11], v[8:11]
	v_mfma_f32_16x16x32_bf16 v[12:15], v[140:143], a[12:15], v[12:15]
	s_waitcnt vmcnt(8)
	s_barrier
	s_add_u32 m0, s52, 0x4000
	s_add_u32 s4, s44, 0x0
	s_addc_u32 s5, s45, 0
	global_load_lds_dwordx4 v224, s[4:5]
	s_add_u32 m0, s52, 0x5000
	s_add_u32 s4, s44, 0x11000
	s_addc_u32 s5, s45, 0
	global_load_lds_dwordx4 v224, s[4:5]
	s_add_u32 m0, s52, 0x6000
	s_add_u32 s4, s46, 0x0
	s_addc_u32 s5, s47, 0
	global_load_lds_dwordx4 v168, s[4:5]
	s_add_u32 m0, s52, 0x7000
	s_add_u32 s4, s46, 0x11000
	s_addc_u32 s5, s47, 0
	global_load_lds_dwordx4 v168, s[4:5]
	s_add_u32 s44, s44, 0x80
	s_addc_u32 s45, s45, 0
	s_add_u32 s46, s46, 0x80
	s_addc_u32 s47, s47, 0
	ds_read_b128 v[204:207], v222 offset:32768
	ds_read_b128 v[208:211], v222 offset:34816
	ds_read_b128 v[212:215], v222 offset:36864
	ds_read_b128 v[216:219], v222 offset:38912
	ds_read_b128 v[136:139], v220 offset:32768
	ds_read_b128 a[0:3], v223 offset:32768
	ds_read_b128 a[4:7], v223 offset:34816
	ds_read_b128 a[8:11], v223 offset:36864
	ds_read_b128 a[12:15], v223 offset:38912
	ds_read_b128 v[140:143], v221 offset:32768
	s_waitcnt lgkmcnt(5)
	v_mfma_f32_16x16x32_bf16 v[0:3], v[136:139], v[204:207], v[0:3]
	v_mfma_f32_16x16x32_bf16 v[4:7], v[136:139], v[208:211], v[4:7]
	v_mfma_f32_16x16x32_bf16 v[8:11], v[136:139], v[212:215], v[8:11]
	v_mfma_f32_16x16x32_bf16 v[12:15], v[136:139], v[216:219], v[12:15]
	s_waitcnt lgkmcnt(0)
	v_mfma_f32_16x16x32_bf16 v[0:3], v[140:143], a[0:3], v[0:3]
	v_mfma_f32_16x16x32_bf16 v[4:7], v[140:143], a[4:7], v[4:7]
	v_mfma_f32_16x16x32_bf16 v[8:11], v[140:143], a[8:11], v[8:11]
	v_mfma_f32_16x16x32_bf16 v[12:15], v[140:143], a[12:15], v[12:15]
	s_waitcnt vmcnt(8)
	s_barrier
	s_add_u32 m0, s52, 0x8000
	s_add_u32 s4, s44, 0x0
	s_addc_u32 s5, s45, 0
	global_load_lds_dwordx4 v224, s[4:5]
	s_add_u32 m0, s52, 0x9000
	s_add_u32 s4, s44, 0x11000
	s_addc_u32 s5, s45, 0
	global_load_lds_dwordx4 v224, s[4:5]
	s_add_u32 m0, s52, 0xa000
	s_add_u32 s4, s46, 0x0
	s_addc_u32 s5, s47, 0
	global_load_lds_dwordx4 v168, s[4:5]
	s_add_u32 m0, s52, 0xb000
	s_add_u32 s4, s46, 0x11000
	s_addc_u32 s5, s47, 0
	global_load_lds_dwordx4 v168, s[4:5]
	s_add_u32 s44, s44, 0x80
	s_addc_u32 s45, s45, 0
	s_add_u32 s46, s46, 0x80
	s_addc_u32 s47, s47, 0
	ds_read_b128 v[204:207], v222 offset:49152
	ds_read_b128 v[208:211], v222 offset:51200
	ds_read_b128 v[212:215], v222 offset:53248
	ds_read_b128 v[216:219], v222 offset:55296
	ds_read_b128 v[136:139], v220 offset:49152
	ds_read_b128 a[0:3], v223 offset:49152
	ds_read_b128 a[4:7], v223 offset:51200
	ds_read_b128 a[8:11], v223 offset:53248
	ds_read_b128 a[12:15], v223 offset:55296
	ds_read_b128 v[140:143], v221 offset:49152
	s_waitcnt lgkmcnt(5)
	v_mfma_f32_16x16x32_bf16 v[0:3], v[136:139], v[204:207], v[0:3]
	v_mfma_f32_16x16x32_bf16 v[4:7], v[136:139], v[208:211], v[4:7]
	v_mfma_f32_16x16x32_bf16 v[8:11], v[136:139], v[212:215], v[8:11]
	v_mfma_f32_16x16x32_bf16 v[12:15], v[136:139], v[216:219], v[12:15]
	s_waitcnt lgkmcnt(0)
	v_mfma_f32_16x16x32_bf16 v[0:3], v[140:143], a[0:3], v[0:3]
	v_mfma_f32_16x16x32_bf16 v[4:7], v[140:143], a[4:7], v[4:7]
	v_mfma_f32_16x16x32_bf16 v[8:11], v[140:143], a[8:11], v[8:11]
	v_mfma_f32_16x16x32_bf16 v[12:15], v[140:143], a[12:15], v[12:15]
	s_waitcnt vmcnt(8)
	s_barrier
	s_add_u32 m0, s52, 0xc000
	s_add_u32 s4, s44, 0x0
	s_addc_u32 s5, s45, 0
	global_load_lds_dwordx4 v224, s[4:5]
	s_add_u32 m0, s52, 0xd000
	s_add_u32 s4, s44, 0x11000
	s_addc_u32 s5, s45, 0
	global_load_lds_dwordx4 v224, s[4:5]
	s_add_u32 m0, s52, 0xe000
	s_add_u32 s4, s46, 0x0
	s_addc_u32 s5, s47, 0
	global_load_lds_dwordx4 v168, s[4:5]
	s_add_u32 m0, s52, 0xf000
	s_add_u32 s4, s46, 0x11000
	s_addc_u32 s5, s47, 0
	global_load_lds_dwordx4 v168, s[4:5]
	s_add_u32 s44, s44, 0x80
	s_addc_u32 s45, s45, 0
	s_add_u32 s46, s46, 0x80
	s_addc_u32 s47, s47, 0
	ds_read_b128 v[204:207], v222
	ds_read_b128 v[208:211], v222 offset:2048
	ds_read_b128 v[212:215], v222 offset:4096
	ds_read_b128 v[216:219], v222 offset:6144
	ds_read_b128 v[136:139], v220
	ds_read_b128 a[0:3], v223
	ds_read_b128 a[4:7], v223 offset:2048
	ds_read_b128 a[8:11], v223 offset:4096
	ds_read_b128 a[12:15], v223 offset:6144
	ds_read_b128 v[140:143], v221
	s_waitcnt lgkmcnt(5)
	v_mfma_f32_16x16x32_bf16 v[0:3], v[136:139], v[204:207], v[0:3]
	v_mfma_f32_16x16x32_bf16 v[4:7], v[136:139], v[208:211], v[4:7]
	v_mfma_f32_16x16x32_bf16 v[8:11], v[136:139], v[212:215], v[8:11]
	v_mfma_f32_16x16x32_bf16 v[12:15], v[136:139], v[216:219], v[12:15]
	s_waitcnt lgkmcnt(0)
	v_mfma_f32_16x16x32_bf16 v[0:3], v[140:143], a[0:3], v[0:3]
	v_mfma_f32_16x16x32_bf16 v[4:7], v[140:143], a[4:7], v[4:7]
	v_mfma_f32_16x16x32_bf16 v[8:11], v[140:143], a[8:11], v[8:11]
	v_mfma_f32_16x16x32_bf16 v[12:15], v[140:143], a[12:15], v[12:15]
	s_waitcnt vmcnt(8)
	s_barrier
	s_add_u32 m0, s52, 0x0
	s_add_u32 s4, s44, 0x0
	s_addc_u32 s5, s45, 0
	global_load_lds_dwordx4 v224, s[4:5]
	s_add_u32 m0, s52, 0x1000
	s_add_u32 s4, s44, 0x11000
	s_addc_u32 s5, s45, 0
	global_load_lds_dwordx4 v224, s[4:5]
	s_add_u32 m0, s52, 0x2000
	s_add_u32 s4, s46, 0x0
	s_addc_u32 s5, s47, 0
	global_load_lds_dwordx4 v168, s[4:5]
	s_add_u32 m0, s52, 0x3000
	s_add_u32 s4, s46, 0x11000
	s_addc_u32 s5, s47, 0
	global_load_lds_dwordx4 v168, s[4:5]
	s_add_u32 s44, s44, 0x80
	s_addc_u32 s45, s45, 0
	s_add_u32 s46, s46, 0x80
	s_addc_u32 s47, s47, 0
	ds_read_b128 v[204:207], v222 offset:16384
	ds_read_b128 v[208:211], v222 offset:18432
	ds_read_b128 v[212:215], v222 offset:20480
	ds_read_b128 v[216:219], v222 offset:22528
	ds_read_b128 v[136:139], v220 offset:16384
	ds_read_b128 a[0:3], v223 offset:16384
	ds_read_b128 a[4:7], v223 offset:18432
	ds_read_b128 a[8:11], v223 offset:20480
	ds_read_b128 a[12:15], v223 offset:22528
	ds_read_b128 v[140:143], v221 offset:16384
	s_waitcnt lgkmcnt(5)
	v_mfma_f32_16x16x32_bf16 v[0:3], v[136:139], v[204:207], v[0:3]
	v_mfma_f32_16x16x32_bf16 v[4:7], v[136:139], v[208:211], v[4:7]
	v_mfma_f32_16x16x32_bf16 v[8:11], v[136:139], v[212:215], v[8:11]
	v_mfma_f32_16x16x32_bf16 v[12:15], v[136:139], v[216:219], v[12:15]
	s_waitcnt lgkmcnt(0)
	v_mfma_f32_16x16x32_bf16 v[0:3], v[140:143], a[0:3], v[0:3]
	v_mfma_f32_16x16x32_bf16 v[4:7], v[140:143], a[4:7], v[4:7]
	v_mfma_f32_16x16x32_bf16 v[8:11], v[140:143], a[8:11], v[8:11]
	v_mfma_f32_16x16x32_bf16 v[12:15], v[140:143], a[12:15], v[12:15]
	s_waitcnt vmcnt(8)
	s_barrier
	s_add_u32 m0, s52, 0x4000
	s_add_u32 s4, s44, 0x0
	s_addc_u32 s5, s45, 0
	global_load_lds_dwordx4 v224, s[4:5]
	s_add_u32 m0, s52, 0x5000
	s_add_u32 s4, s44, 0x11000
	s_addc_u32 s5, s45, 0
	global_load_lds_dwordx4 v224, s[4:5]
	s_add_u32 m0, s52, 0x6000
	s_add_u32 s4, s46, 0x0
	s_addc_u32 s5, s47, 0
	global_load_lds_dwordx4 v168, s[4:5]
	s_add_u32 m0, s52, 0x7000
	s_add_u32 s4, s46, 0x11000
	s_addc_u32 s5, s47, 0
	global_load_lds_dwordx4 v168, s[4:5]
	s_add_u32 s44, s44, 0x80
	s_addc_u32 s45, s45, 0
	s_add_u32 s46, s46, 0x80
	s_addc_u32 s47, s47, 0
	ds_read_b128 v[204:207], v222 offset:32768
	ds_read_b128 v[208:211], v222 offset:34816
	ds_read_b128 v[212:215], v222 offset:36864
	ds_read_b128 v[216:219], v222 offset:38912
	ds_read_b128 v[136:139], v220 offset:32768
	ds_read_b128 a[0:3], v223 offset:32768
	ds_read_b128 a[4:7], v223 offset:34816
	ds_read_b128 a[8:11], v223 offset:36864
	ds_read_b128 a[12:15], v223 offset:38912
	ds_read_b128 v[140:143], v221 offset:32768
	s_waitcnt lgkmcnt(5)
	v_mfma_f32_16x16x32_bf16 v[0:3], v[136:139], v[204:207], v[0:3]
	v_mfma_f32_16x16x32_bf16 v[4:7], v[136:139], v[208:211], v[4:7]
	v_mfma_f32_16x16x32_bf16 v[8:11], v[136:139], v[212:215], v[8:11]
	v_mfma_f32_16x16x32_bf16 v[12:15], v[136:139], v[216:219], v[12:15]
	s_waitcnt lgkmcnt(0)
	v_mfma_f32_16x16x32_bf16 v[0:3], v[140:143], a[0:3], v[0:3]
	v_mfma_f32_16x16x32_bf16 v[4:7], v[140:143], a[4:7], v[4:7]
	v_mfma_f32_16x16x32_bf16 v[8:11], v[140:143], a[8:11], v[8:11]
	v_mfma_f32_16x16x32_bf16 v[12:15], v[140:143], a[12:15], v[12:15]
	s_waitcnt vmcnt(8)
	s_barrier
	s_add_u32 m0, s52, 0x8000
	s_add_u32 s4, s44, 0x0
	s_addc_u32 s5, s45, 0
	global_load_lds_dwordx4 v224, s[4:5]
	s_add_u32 m0, s52, 0x9000
	s_add_u32 s4, s44, 0x11000
	s_addc_u32 s5, s45, 0
	global_load_lds_dwordx4 v224, s[4:5]
	s_add_u32 m0, s52, 0xa000
	s_add_u32 s4, s46, 0x0
	s_addc_u32 s5, s47, 0
	global_load_lds_dwordx4 v168, s[4:5]
	s_add_u32 m0, s52, 0xb000
	s_add_u32 s4, s46, 0x11000
	s_addc_u32 s5, s47, 0
	global_load_lds_dwordx4 v168, s[4:5]
	s_add_u32 s44, s44, 0x80
	s_addc_u32 s45, s45, 0
	s_add_u32 s46, s46, 0x80
	s_addc_u32 s47, s47, 0
	ds_read_b128 v[204:207], v222 offset:49152
	ds_read_b128 v[208:211], v222 offset:51200
	ds_read_b128 v[212:215], v222 offset:53248
	ds_read_b128 v[216:219], v222 offset:55296
	ds_read_b128 v[136:139], v220 offset:49152
	ds_read_b128 a[0:3], v223 offset:49152
	ds_read_b128 a[4:7], v223 offset:51200
	ds_read_b128 a[8:11], v223 offset:53248
	ds_read_b128 a[12:15], v223 offset:55296
	ds_read_b128 v[140:143], v221 offset:49152
	s_waitcnt lgkmcnt(5)
	v_mfma_f32_16x16x32_bf16 v[0:3], v[136:139], v[204:207], v[0:3]
	v_mfma_f32_16x16x32_bf16 v[4:7], v[136:139], v[208:211], v[4:7]
	v_mfma_f32_16x16x32_bf16 v[8:11], v[136:139], v[212:215], v[8:11]
	v_mfma_f32_16x16x32_bf16 v[12:15], v[136:139], v[216:219], v[12:15]
	s_waitcnt lgkmcnt(0)
	v_mfma_f32_16x16x32_bf16 v[0:3], v[140:143], a[0:3], v[0:3]
	v_mfma_f32_16x16x32_bf16 v[4:7], v[140:143], a[4:7], v[4:7]
	v_mfma_f32_16x16x32_bf16 v[8:11], v[140:143], a[8:11], v[8:11]
	v_mfma_f32_16x16x32_bf16 v[12:15], v[140:143], a[12:15], v[12:15]
	s_waitcnt vmcnt(8)
	s_barrier
	s_add_u32 m0, s52, 0xc000
	s_add_u32 s4, s44, 0x0
	s_addc_u32 s5, s45, 0
	global_load_lds_dwordx4 v224, s[4:5]
	s_add_u32 m0, s52, 0xd000
	s_add_u32 s4, s44, 0x11000
	s_addc_u32 s5, s45, 0
	global_load_lds_dwordx4 v224, s[4:5]
	s_add_u32 m0, s52, 0xe000
	s_add_u32 s4, s46, 0x0
	s_addc_u32 s5, s47, 0
	global_load_lds_dwordx4 v168, s[4:5]
	s_add_u32 m0, s52, 0xf000
	s_add_u32 s4, s46, 0x11000
	s_addc_u32 s5, s47, 0
	global_load_lds_dwordx4 v168, s[4:5]
	s_add_u32 s44, s44, 0x80
	s_addc_u32 s45, s45, 0
	s_add_u32 s46, s46, 0x80
	s_addc_u32 s47, s47, 0
	ds_read_b128 v[204:207], v222
	ds_read_b128 v[208:211], v222 offset:2048
	ds_read_b128 v[212:215], v222 offset:4096
	ds_read_b128 v[216:219], v222 offset:6144
	ds_read_b128 v[136:139], v220
	ds_read_b128 a[0:3], v223
	ds_read_b128 a[4:7], v223 offset:2048
	ds_read_b128 a[8:11], v223 offset:4096
	ds_read_b128 a[12:15], v223 offset:6144
	ds_read_b128 v[140:143], v221
	s_waitcnt lgkmcnt(5)
	v_mfma_f32_16x16x32_bf16 v[0:3], v[136:139], v[204:207], v[0:3]
	v_mfma_f32_16x16x32_bf16 v[4:7], v[136:139], v[208:211], v[4:7]
	v_mfma_f32_16x16x32_bf16 v[8:11], v[136:139], v[212:215], v[8:11]
	v_mfma_f32_16x16x32_bf16 v[12:15], v[136:139], v[216:219], v[12:15]
	s_waitcnt lgkmcnt(0)
	v_mfma_f32_16x16x32_bf16 v[0:3], v[140:143], a[0:3], v[0:3]
	v_mfma_f32_16x16x32_bf16 v[4:7], v[140:143], a[4:7], v[4:7]
	v_mfma_f32_16x16x32_bf16 v[8:11], v[140:143], a[8:11], v[8:11]
	v_mfma_f32_16x16x32_bf16 v[12:15], v[140:143], a[12:15], v[12:15]
	s_waitcnt vmcnt(8)
	s_barrier
	ds_read_b128 v[204:207], v222 offset:16384
	ds_read_b128 v[208:211], v222 offset:18432
	ds_read_b128 v[212:215], v222 offset:20480
	ds_read_b128 v[216:219], v222 offset:22528
	ds_read_b128 v[136:139], v220 offset:16384
	ds_read_b128 a[0:3], v223 offset:16384
	ds_read_b128 a[4:7], v223 offset:18432
	ds_read_b128 a[8:11], v223 offset:20480
	ds_read_b128 a[12:15], v223 offset:22528
	ds_read_b128 v[140:143], v221 offset:16384
	s_waitcnt lgkmcnt(5)
	v_mfma_f32_16x16x32_bf16 v[0:3], v[136:139], v[204:207], v[0:3]
	v_mfma_f32_16x16x32_bf16 v[4:7], v[136:139], v[208:211], v[4:7]
	v_mfma_f32_16x16x32_bf16 v[8:11], v[136:139], v[212:215], v[8:11]
	v_mfma_f32_16x16x32_bf16 v[12:15], v[136:139], v[216:219], v[12:15]
	s_waitcnt lgkmcnt(0)
	v_mfma_f32_16x16x32_bf16 v[0:3], v[140:143], a[0:3], v[0:3]
	v_mfma_f32_16x16x32_bf16 v[4:7], v[140:143], a[4:7], v[4:7]
	v_mfma_f32_16x16x32_bf16 v[8:11], v[140:143], a[8:11], v[8:11]
	v_mfma_f32_16x16x32_bf16 v[12:15], v[140:143], a[12:15], v[12:15]
	s_waitcnt vmcnt(4)
	s_barrier
	ds_read_b128 v[204:207], v222 offset:32768
	ds_read_b128 v[208:211], v222 offset:34816
	ds_read_b128 v[212:215], v222 offset:36864
	ds_read_b128 v[216:219], v222 offset:38912
	ds_read_b128 v[136:139], v220 offset:32768
	ds_read_b128 a[0:3], v223 offset:32768
	ds_read_b128 a[4:7], v223 offset:34816
	ds_read_b128 a[8:11], v223 offset:36864
	ds_read_b128 a[12:15], v223 offset:38912
	ds_read_b128 v[140:143], v221 offset:32768
	s_waitcnt lgkmcnt(5)
	v_mfma_f32_16x16x32_bf16 v[0:3], v[136:139], v[204:207], v[0:3]
	v_mfma_f32_16x16x32_bf16 v[4:7], v[136:139], v[208:211], v[4:7]
	v_mfma_f32_16x16x32_bf16 v[8:11], v[136:139], v[212:215], v[8:11]
	v_mfma_f32_16x16x32_bf16 v[12:15], v[136:139], v[216:219], v[12:15]
	s_waitcnt lgkmcnt(0)
	v_mfma_f32_16x16x32_bf16 v[0:3], v[140:143], a[0:3], v[0:3]
	v_mfma_f32_16x16x32_bf16 v[4:7], v[140:143], a[4:7], v[4:7]
	v_mfma_f32_16x16x32_bf16 v[8:11], v[140:143], a[8:11], v[8:11]
	v_mfma_f32_16x16x32_bf16 v[12:15], v[140:143], a[12:15], v[12:15]
	s_waitcnt vmcnt(0)
	s_barrier
	ds_read_b128 v[204:207], v222 offset:49152
	ds_read_b128 v[208:211], v222 offset:51200
	ds_read_b128 v[212:215], v222 offset:53248
	ds_read_b128 v[216:219], v222 offset:55296
	ds_read_b128 v[136:139], v220 offset:49152
	ds_read_b128 a[0:3], v223 offset:49152
	ds_read_b128 a[4:7], v223 offset:51200
	ds_read_b128 a[8:11], v223 offset:53248
	ds_read_b128 a[12:15], v223 offset:55296
	ds_read_b128 v[140:143], v221 offset:49152
	s_waitcnt lgkmcnt(5)
	v_mfma_f32_16x16x32_bf16 v[0:3], v[136:139], v[204:207], v[0:3]
	v_mfma_f32_16x16x32_bf16 v[4:7], v[136:139], v[208:211], v[4:7]
	v_mfma_f32_16x16x32_bf16 v[8:11], v[136:139], v[212:215], v[8:11]
	v_mfma_f32_16x16x32_bf16 v[12:15], v[136:139], v[216:219], v[12:15]
	s_waitcnt lgkmcnt(0)
	v_mfma_f32_16x16x32_bf16 v[0:3], v[140:143], a[0:3], v[0:3]
	v_mfma_f32_16x16x32_bf16 v[4:7], v[140:143], a[4:7], v[4:7]
	v_mfma_f32_16x16x32_bf16 v[8:11], v[140:143], a[8:11], v[8:11]
	v_mfma_f32_16x16x32_bf16 v[12:15], v[140:143], a[12:15], v[12:15]
	s_nop 7
	s_nop 7
	v_mov_b32_e32 v226, s50
	v_mov_b32_e32 v227, s51
	v_add_co_u32_e32 v226, vcc, v226, v225
	s_nop 1
	v_addc_co_u32_e32 v227, vcc, 0, v227, vcc
	v_mul_f32_e32 v228, 0xbfb8aa3b, v0
	v_exp_f32_e32 v228, v228
	s_nop 0
	v_add_f32_e32 v229, 1.0, v228
	v_div_scale_f32 v230, s[4:5], v229, v229, v0
	v_rcp_f32_e32 v231, v230
	v_div_scale_f32 v232, vcc, v0, v229, v0
	v_fma_f32 v131, -v230, v231, 1.0
	v_fmac_f32_e32 v231, v131, v231
	v_mul_f32_e32 v233, v232, v231
	v_fma_f32 v131, -v230, v233, v232
	v_fmac_f32_e32 v233, v131, v231
	v_fma_f32 v230, -v230, v233, v232
	v_div_fmas_f32 v230, v230, v231, v233
	v_div_fixup_f32 v135, v230, v229, v0
	v_mul_f32_e32 v135, v8, v135
	v_mul_f32_e32 v228, 0xbfb8aa3b, v4
	v_exp_f32_e32 v228, v228
	s_nop 0
	v_add_f32_e32 v229, 1.0, v228
	v_div_scale_f32 v230, s[4:5], v229, v229, v4
	v_rcp_f32_e32 v231, v230
	v_div_scale_f32 v232, vcc, v4, v229, v4
	v_fma_f32 v131, -v230, v231, 1.0
	v_fmac_f32_e32 v231, v131, v231
	v_mul_f32_e32 v233, v232, v231
	v_fma_f32 v131, -v230, v233, v232
	v_fmac_f32_e32 v233, v131, v231
	v_fma_f32 v230, -v230, v233, v232
	v_div_fmas_f32 v230, v230, v231, v233
	v_div_fixup_f32 v133, v230, v229, v4
	v_mul_f32_e32 v133, v12, v133
	v_cvt_pk_bf16_f32 v133, v135, v133
	global_store_dword v[226:227], v133, off
	s_mov_b64 s[40:41], 0x1680
	v_lshl_add_u64 v[226:227], v[226:227], 0, s[40:41]
	v_mul_f32_e32 v228, 0xbfb8aa3b, v1
	v_exp_f32_e32 v228, v228
	s_nop 0
	v_add_f32_e32 v229, 1.0, v228
	v_div_scale_f32 v230, s[4:5], v229, v229, v1
	v_rcp_f32_e32 v231, v230
	v_div_scale_f32 v232, vcc, v1, v229, v1
	v_fma_f32 v131, -v230, v231, 1.0
	v_fmac_f32_e32 v231, v131, v231
	v_mul_f32_e32 v233, v232, v231
	v_fma_f32 v131, -v230, v233, v232
	v_fmac_f32_e32 v233, v131, v231
	v_fma_f32 v230, -v230, v233, v232
	v_div_fmas_f32 v230, v230, v231, v233
	v_div_fixup_f32 v135, v230, v229, v1
	v_mul_f32_e32 v135, v9, v135
	v_mul_f32_e32 v228, 0xbfb8aa3b, v5
	v_exp_f32_e32 v228, v228
	s_nop 0
	v_add_f32_e32 v229, 1.0, v228
	v_div_scale_f32 v230, s[4:5], v229, v229, v5
	v_rcp_f32_e32 v231, v230
	v_div_scale_f32 v232, vcc, v5, v229, v5
	v_fma_f32 v131, -v230, v231, 1.0
	v_fmac_f32_e32 v231, v131, v231
	v_mul_f32_e32 v233, v232, v231
	v_fma_f32 v131, -v230, v233, v232
	v_fmac_f32_e32 v233, v131, v231
	v_fma_f32 v230, -v230, v233, v232
	v_div_fmas_f32 v230, v230, v231, v233
	v_div_fixup_f32 v133, v230, v229, v5
	v_mul_f32_e32 v133, v13, v133
	v_cvt_pk_bf16_f32 v133, v135, v133
	global_store_dword v[226:227], v133, off
	s_mov_b64 s[40:41], 0x1680
	v_lshl_add_u64 v[226:227], v[226:227], 0, s[40:41]
	v_mul_f32_e32 v228, 0xbfb8aa3b, v2
	v_exp_f32_e32 v228, v228
	s_nop 0
	v_add_f32_e32 v229, 1.0, v228
	v_div_scale_f32 v230, s[4:5], v229, v229, v2
	v_rcp_f32_e32 v231, v230
	v_div_scale_f32 v232, vcc, v2, v229, v2
	v_fma_f32 v131, -v230, v231, 1.0
	v_fmac_f32_e32 v231, v131, v231
	v_mul_f32_e32 v233, v232, v231
	v_fma_f32 v131, -v230, v233, v232
	v_fmac_f32_e32 v233, v131, v231
	v_fma_f32 v230, -v230, v233, v232
	v_div_fmas_f32 v230, v230, v231, v233
	v_div_fixup_f32 v135, v230, v229, v2
	v_mul_f32_e32 v135, v10, v135
	v_mul_f32_e32 v228, 0xbfb8aa3b, v6
	v_exp_f32_e32 v228, v228
	s_nop 0
	v_add_f32_e32 v229, 1.0, v228
	v_div_scale_f32 v230, s[4:5], v229, v229, v6
	v_rcp_f32_e32 v231, v230
	v_div_scale_f32 v232, vcc, v6, v229, v6
	v_fma_f32 v131, -v230, v231, 1.0
	v_fmac_f32_e32 v231, v131, v231
	v_mul_f32_e32 v233, v232, v231
	v_fma_f32 v131, -v230, v233, v232
	v_fmac_f32_e32 v233, v131, v231
	v_fma_f32 v230, -v230, v233, v232
	v_div_fmas_f32 v230, v230, v231, v233
	v_div_fixup_f32 v133, v230, v229, v6
	v_mul_f32_e32 v133, v14, v133
	v_cvt_pk_bf16_f32 v133, v135, v133
	global_store_dword v[226:227], v133, off
	s_mov_b64 s[40:41], 0x1680
	v_lshl_add_u64 v[226:227], v[226:227], 0, s[40:41]
	v_mul_f32_e32 v228, 0xbfb8aa3b, v3
	v_exp_f32_e32 v228, v228
	s_nop 0
	v_add_f32_e32 v229, 1.0, v228
	v_div_scale_f32 v230, s[4:5], v229, v229, v3
	v_rcp_f32_e32 v231, v230
	v_div_scale_f32 v232, vcc, v3, v229, v3
	v_fma_f32 v131, -v230, v231, 1.0
	v_fmac_f32_e32 v231, v131, v231
	v_mul_f32_e32 v233, v232, v231
	v_fma_f32 v131, -v230, v233, v232
	v_fmac_f32_e32 v233, v131, v231
	v_fma_f32 v230, -v230, v233, v232
	v_div_fmas_f32 v230, v230, v231, v233
	v_div_fixup_f32 v135, v230, v229, v3
	v_mul_f32_e32 v135, v11, v135
	v_mul_f32_e32 v228, 0xbfb8aa3b, v7
	v_exp_f32_e32 v228, v228
	s_nop 0
	v_add_f32_e32 v229, 1.0, v228
	v_div_scale_f32 v230, s[4:5], v229, v229, v7
	v_rcp_f32_e32 v231, v230
	v_div_scale_f32 v232, vcc, v7, v229, v7
	v_fma_f32 v131, -v230, v231, 1.0
	v_fmac_f32_e32 v231, v131, v231
	v_mul_f32_e32 v233, v232, v231
	v_fma_f32 v131, -v230, v233, v232
	v_fmac_f32_e32 v233, v131, v231
	v_fma_f32 v230, -v230, v233, v232
	v_div_fmas_f32 v230, v230, v231, v233
	v_div_fixup_f32 v133, v230, v229, v7
	v_mul_f32_e32 v133, v15, v133
	v_cvt_pk_bf16_f32 v133, v135, v133
	global_store_dword v[226:227], v133, off
	s_branch .Lfp_next
